# dense attention item loop shifted +32 bytes (loop-head offset 28 mod 64 instead of 60), downstream addresses kept by a complementary pad after the phase
# speedup vs baseline: 1.0065x; 1.0065x over previous
; DI int fresh_lane() { int l; asm volatile("v_mbcnt_lo_u32_b32 %0, -1, 0\n\tv_mbcnt_hi_u32_b32 %0, -1, %0" : "=v"(l)); return l; }
; #define FRESH_IDS() int tid_ = wave_s * 64 + fresh_lane(); asm volatile("" : "+v"(tid_)); const int tid = tid_, lane = tid & 63, wave = wave_s; (void)tid; (void)lane; (void)wave
; __global__ void __launch_bounds__(512, 2) fwd_kernel(Params p) {
;     ...
;     for (int rep_ = 0; rep_ < REP_ATTNC; ++rep_) { FRESH_IDS();
;         const int G_ = (int)gridDim.x, vcu = (G_ % 8 == 0) ? ((int)blockIdx.x & 7) * (G_ >> 3) + ((int)blockIdx.x >> 3) : (int)blockIdx.x;
;         for (int item = vcu; item < 1024; item += G_) {
;             const int qb = item & 15, head = (item >> 4) & 7, b = item >> 7, kvh = head >> 2;
;             int tl = wave * 64 + fresh_lane(); asm volatile("" : "+v"(tl));
;             const size_t qrow = (size_t)NCTX + (size_t)b * SEQ + qb * 256;
;             __syncthreads();
.LBB0_1525:
	s_or_b64 exec, exec, s[0:1]
	s_and_b32 s1, s75, 7
	s_ashr_i32 s2, s30, 3
	s_mul_i32 s1, s2, s1
	s_ashr_i32 s2, s75, 3
	s_and_b32 s0, s30, 7
	s_add_i32 s1, s1, s2
	s_cmp_eq_u32 s0, 0
	s_waitcnt lgkmcnt(0)
	s_barrier
	v_mbcnt_lo_u32_b32 v0, -1, 0
	v_mbcnt_hi_u32_b32 v0, -1, v0
	s_cselect_b32 s2, s1, s75
	s_mov_b32 s56, 0
	v_add_u32_e32 v0, s74, v0
	s_cmpk_gt_i32 s2, 0x3ff
	s_cbranch_scc1 .LBB0_1547
	s_add_u32 s3, s28, 0x1e500000
	s_addc_u32 s11, s29, 0
	s_add_u32 s0, s28, 0x1e512000
	s_addc_u32 s1, s29, 0
	v_mov_b32_e32 v177, 0
	s_mov_b32 s14, 0x42b504f3
	s_mov_b32 s10, 0x3e0293ee
	v_mov_b32_e32 v180, 0xf149f2ca
	s_mov_b64 s[12:13], 0x8000
	v_mov_b32_e32 v181, 0x110000
	s_nop 0
	s_nop 0
	s_nop 0
	s_nop 0
	s_nop 0
	s_nop 0
	s_nop 0
	s_nop 0
	s_branch .LBB0_1528

; DI void xcd_barrier(const XcdBarrier& b, int tid) {
;     asm volatile("s_waitcnt vmcnt(0)" ::: "memory");
;     __syncthreads();
;     if (tid == 0) {
;         unsigned* bar = b.bar;
;         __builtin_amdgcn_s_waitcnt(0);
;         unsigned nloc = b.st[0], nx = b.st[1];
;         if (nloc == 0u) { xcd_barrier_complete(bar, b.x, nloc, nx); b.st[0] = nloc; b.st[1] = nx; }
.LBB0_1547:
	s_nop 0
	s_nop 0
	s_nop 0
	s_nop 0
	s_nop 0
	s_nop 0
	s_nop 0
	s_nop 0
	v_mbcnt_lo_u32_b32 v0, -1, 0
	v_mbcnt_hi_u32_b32 v0, -1, v0
	s_nop 0
	v_add_u32_e32 v0, s74, v0
	s_waitcnt vmcnt(0)
	s_waitcnt vmcnt(63) expcnt(7) lgkmcnt(15)
	v_cmp_eq_u32_e32 vcc, 0, v0
	s_barrier
	s_and_saveexec_b64 s[0:1], vcc
	v_readlane_b32 s59, v254, 12
	s_cbranch_execz .LBB0_1599
	s_add_i32 s2, 0, 0x23ff0
	v_mov_b32_e32 v0, s2
	s_waitcnt vmcnt(0) expcnt(0) lgkmcnt(0)
	ds_read_b32 v2, v0
	s_add_i32 s2, 0, 0x23ff4
	v_mov_b32_e32 v0, s2
	ds_read_b32 v0, v0
	s_waitcnt lgkmcnt(1)
	v_cmp_ne_u32_e32 vcc, 0, v2
	s_cbranch_vccnz .LBB0_1563
	s_mov_b32 s2, 1
	v_mov_b32_e32 v16, 0
	s_branch .LBB0_1551
